# P3a->P4 grid barrier: non-scan workgroups arrive without waiting; next-layer weight conversion dealt to non-scan workgroups only; P7 sc/sh loads hoisted
# speedup vs baseline: 1.0734x; 1.0052x over previous
; DI unsigned xb_ld(unsigned* p)              { return __hip_atomic_load(p, __ATOMIC_RELAXED, __HIP_MEMORY_SCOPE_AGENT); }
; DI unsigned xb_add(unsigned* p, unsigned v) { return __hip_atomic_fetch_add(p, v, __ATOMIC_RELAXED, __HIP_MEMORY_SCOPE_AGENT); }
; #define XB_SPIN(cond, bar) do { unsigned _sp = 0; while (cond) { __builtin_amdgcn_s_sleep(1); \
;     if ((++_sp & 255u) == 0u) { if (xb_ld(&(bar)[XB_TMO])) break; if (_sp > XB_SPIN_CAP) { atomicAdd(&(bar)[XB_TMO], 1u); break; } } } } while (0)
; DI void xcd_barrier(const XcdBarrier& b, int wid_k) {
;     ...
;         unsigned nloc = b.st[0], nx = b.st[1];
;         if (nloc == 0u) { xcd_barrier_complete(bar, b.x, nloc, nx); b.st[0] = nloc; b.st[1] = nx; }
;         const unsigned old = xb_add(&bar[XB_XSUB(b.x)], 1u);
;         const unsigned gen = old / nloc;
;         if (old + 1u == (gen + 1u) * nloc) {
;             __builtin_amdgcn_fence(__ATOMIC_RELEASE, "agent");
;             asm volatile("s_waitcnt vmcnt(0)" ::: "memory");
;             const unsigned og = xb_add(&bar[XB_TOP], 1u);
;             const unsigned tg = og / nx;
;             if (og + 1u == (tg + 1u) * nx) xb_add(&bar[XB_TOPGEN], 1u);
;             else XB_SPIN(xb_ld(&bar[XB_TOPGEN]) == tg, bar);
;             __builtin_amdgcn_fence(__ATOMIC_ACQUIRE, "agent");
;             xb_add(&bar[XB_XGEN(b.x)], 1u);
;             asm volatile("s_waitcnt vmcnt(0)" ::: "memory");
;         } else {
;             XB_SPIN(xb_ld(&bar[XB_XGEN(b.x)]) == gen, bar);
.LBB0_516:
	s_or_b64 exec, exec, s[8:9]
	v_cvt_f32_u32_e32 v5, v3
	s_waitcnt vmcnt(0)
	v_readfirstlane_b32 s6, v4
	v_sub_u32_e32 v4, 0, v3
	v_rcp_iflag_f32_e32 v5, v5
	v_add_u32_e32 v6, s6, v0
	v_mul_f32_e32 v5, 0x4f7ffffe, v5
	v_cvt_u32_f32_e32 v5, v5
	v_mul_lo_u32 v0, v4, v5
	v_mul_hi_u32 v0, v5, v0
	v_add_u32_e32 v0, v5, v0
	v_mul_hi_u32 v0, v6, v0
	v_mul_lo_u32 v4, v0, v3
	v_sub_u32_e32 v4, v6, v4
	v_add_u32_e32 v5, 1, v0
	v_cmp_ge_u32_e32 vcc, v4, v3
	s_nop 1
	v_cndmask_b32_e32 v0, v0, v5, vcc
	v_sub_u32_e32 v5, v4, v3
	v_cndmask_b32_e32 v4, v4, v5, vcc
	v_add_u32_e32 v5, 1, v0
	v_cmp_ge_u32_e32 vcc, v4, v3
	v_add_u32_e32 v4, 1, v6
	s_nop 0
	v_cndmask_b32_e32 v0, v0, v5, vcc
	v_mul_lo_u32 v5, v3, v0
	v_add_u32_e32 v3, v5, v3
	v_cmp_ne_u32_e32 vcc, v4, v3
	s_and_saveexec_b64 s[6:7], vcc
	s_xor_b64 s[6:7], exec, s[6:7]
	s_cbranch_execz .LBB0_530
	s_cmp_gt_u32 s33, 63
	s_cbranch_scc1 .Lp3a_nowait
	s_waitcnt lgkmcnt(0)
	global_load_dword v2, v228, s[4:5] offset:1024 sc1
	s_add_u32 s10, s4, 0x2400
	s_addc_u32 s11, s5, 0
	s_waitcnt vmcnt(0)
	v_cmp_eq_u32_e32 vcc, v2, v0
	s_and_saveexec_b64 s[8:9], vcc
	s_cbranch_execz .LBB0_529
	s_mov_b32 s22, 1
	s_mov_b64 s[12:13], 0
	s_branch .LBB0_520

; DI unsigned xb_ld(unsigned* p)              { return __hip_atomic_load(p, __ATOMIC_RELAXED, __HIP_MEMORY_SCOPE_AGENT); }
; #define XB_SPIN(cond, bar) do { unsigned _sp = 0; while (cond) { __builtin_amdgcn_s_sleep(1); \
;     if ((++_sp & 255u) == 0u) { if (xb_ld(&(bar)[XB_TMO])) break; if (_sp > XB_SPIN_CAP) { atomicAdd(&(bar)[XB_TMO], 1u); break; } } } } while (0)
; DI void xcd_barrier(const XcdBarrier& b, int wid_k) {
;     ...
;             XB_SPIN(xb_ld(&bar[XB_XGEN(b.x)]) == gen, bar);
;             __builtin_amdgcn_fence(__ATOMIC_ACQUIRE, "agent");
;             asm volatile("s_waitcnt vmcnt(0)" ::: "memory");
.Lp3a_nowait:
	s_waitcnt vmcnt(0)
	buffer_inv sc1
	s_waitcnt vmcnt(0)

; __global__ void __launch_bounds__(NTHR, 2) fwd_kernel(Params p) {
;     ...
;     {
;     PHASE_BEGIN();
;     unsigned* ctl = WSP(unsigned, OFF_CTL);
;     for (;;) {
;       __syncthreads();
;       if (tid == 0) ((volatile unsigned*)ldsmisc)[256] = atomicAdd(&ctl[64 + l], 1u);
;       __syncthreads();
;       const unsigned it = ((volatile unsigned*)ldsmisc)[256];
;       if (it >= 512u) break;
;       if (it < 256u) { const int qb = 15 - (int)(it >> 4), bh = it & 15; attn_item<192, 128, false>(lds, WSP(u16, OFF_MQ), WSP(u16, OFF_MK), WSP(u16, OFF_MVT), nullptr, WSP(u16, OFF_YC), 512, bh, qb, wid_k); }
;       else { const unsigned i2 = it - 256u; const int qb = 15 - (int)(i2 >> 4), bh = i2 & 15; attn_item<64, 64, true>(lds, WSP(u16, OFF_FQ), WSP(u16, OFF_FK), WSP(u16, OFF_FVT), WSP(float, OFF_CUM), WSP(u16, OFF_YB), 256, bh, qb, wid_k); }
;     }
;     if (l < 3) { const int ln = l + 1; const size_t wseln = (ln & 1) ? (size_t)(WS_END - OFF_WIN) : (size_t)0; __syncthreads(); CONVERT_LAYER(ln, wseln); }
.LBB0_1314:
	s_mov_b32 s95, s73
	s_mov_b64 s[10:11], 0
	s_mov_b32 s6, s73
	s_mov_b64 s[8:9], s[42:43]
	s_lshl_b64 s[4:5], s[94:95], 2
	s_add_u32 s14, s8, s4
	s_addc_u32 s15, s9, s5
	s_add_u32 s16, s8, 0x166a0000
	s_addc_u32 s17, s9, 0
	s_add_u32 s18, s8, 0x16ea0000
	s_addc_u32 s19, s9, 0
	s_add_u32 s20, s8, 0x176a0000
	s_addc_u32 s21, s9, 0
	s_add_u32 s22, s8, 0x7b0000
	s_addc_u32 s23, s9, 0
	s_add_u32 s24, s8, 0x98a0000
	s_addc_u32 s25, s9, 0
	s_add_u32 s26, s8, 0x126a0000
	s_addc_u32 s27, s9, 0
	s_add_u32 s28, s8, 0x13ea0000
	s_addc_u32 s29, s9, 0
	s_add_u32 s30, s8, 0x156a0000
	s_addc_u32 s31, s9, 0
	v_mbcnt_lo_u32_b32 v0, -1, 0
	v_mbcnt_hi_u32_b32 v0, -1, v0
	s_add_u32 s34, s8, 0xd6a0000
	v_or_b32_e32 v183, s97, v0
	s_mov_b64 s[12:13], 0
	s_mov_b32 s63, s33
	s_mov_b32 s62, s44
	v_cmp_eq_u32_e64 s[2:3], 0, v183
	s_addc_u32 s35, s9, 0
	s_sub_i32 s63, s33, 64
	s_cmp_lt_u32 s33, 64
	s_cselect_b32 s63, 0x10000, s63
	s_movk_i32 s62, 0xc0
	s_branch .LBB0_1318

; DI float bflo(unsigned u) { return __uint_as_float(u << 16); }
; DI float bfhi(unsigned u) { return __uint_as_float(u & 0xffff0000u); }
; DI void rowwise_phase(const float* __restrict__ xin, float* __restrict__ xout, const u16* __restrict__ tbuf, ...
;     ...
;   for (int row = gw; row < T; row += nw) {
;     const int b = row >> 12;
;     float4 xv[4];
; #pragma unroll
;     for (int i = 0; i < 4; ++i) { const f32x4 t_ = __builtin_nontemporal_load((const f32x4*)(xin + (size_t)row * 1024 + i * 256 + lane * 4)); xv[i] = make_float4(t_[0], t_[1], t_[2], t_[3]); }
;     if (tbuf) {
;       float4 tv[4]; float ss = 0.f;
; #pragma unroll
;       for (int i = 0; i < 4; ++i) {
;         typedef unsigned u32x2_ __attribute__((ext_vector_type(2)));
;         const u32x2_ u_ = __builtin_nontemporal_load((const u32x2_*)(tbuf + (size_t)row * 1024 + i * 256 + lane * 4)); const uint2 u = make_uint2(u_[0], u_[1]);
;         tv[i] = make_float4(bflo(u.x), bfhi(u.x), bflo(u.y), bfhi(u.y));
;         ss += tv[i].x * tv[i].x + tv[i].y * tv[i].y + tv[i].z * tv[i].z + tv[i].w * tv[i].w;
;       }
;       ss = wave_sum(ss);
;       const float rstd = rsqrtf(ss * (1.f / 1024.f) + 1e-6f);
; #pragma unroll
;       for (int i = 0; i < 4; ++i) {
;         const int c = i * 256 + lane * 4;
;         const float4 g = *(const float4*)(gate + (size_t)b * 6144 + c);
;         const float4 pg = *(const float4*)(pgain + c);
;         xv[i].x += g.x * (tv[i].x * rstd) * pg.x; xv[i].y += g.y * (tv[i].y * rstd) * pg.y;
;         xv[i].z += g.z * (tv[i].z * rstd) * pg.z; xv[i].w += g.w * (tv[i].w * rstd) * pg.w;
;       }
;     }
; #pragma unroll
;     for (int i = 0; i < 4; ++i) { const f32x4 t_ = {xv[i].x, xv[i].y, xv[i].z, xv[i].w}; __builtin_nontemporal_store(t_, (f32x4*)(xout + (size_t)row * 1024 + i * 256 + lane * 4)); }
;     if (hbuf) {
;       float ss = 0.f;
; #pragma unroll
;       for (int i = 0; i < 4; ++i) ss += xv[i].x * xv[i].x + xv[i].y * xv[i].y + xv[i].z * xv[i].z + xv[i].w * xv[i].w;
;       ss = wave_sum(ss);
;       const float rstd = rsqrtf(ss * (1.f / 1024.f) + 1e-6f);
.LBB0_1779:
	v_add_co_u32_e32 v42, vcc, 0xfc000000, v58
	global_load_dwordx4 v[34:37], v[56:57], off offset:-2048 nt
	global_load_dwordx4 v[38:41], v[56:57], off offset:-1024 nt
	global_load_dwordx4 v[66:69], v[56:57], off nt
	global_load_dwordx4 v[70:73], v[56:57], off offset:1024 nt
	v_addc_co_u32_e32 v43, vcc, -1, v59, vcc
	global_load_dwordx2 v[46:47], v[42:43], off offset:-1540 nt
	global_load_dwordx2 v[48:49], v[42:43], off offset:-1028 nt
	global_load_dwordx2 v[62:63], v[42:43], off offset:-516 nt
	global_load_dwordx2 v[86:87], v[42:43], off offset:-4 nt
	v_ashrrev_i32_e32 v60, 12, v64
	v_mul_hi_i32_i24_e32 v43, 0x6000, v60
	v_mul_i32_i24_e32 v42, 0x6000, v60
	v_lshl_add_u64 v[82:83], v[50:51], 0, v[42:43]
	global_load_dwordx4 v[42:45], v[82:83], off
	global_load_dwordx4 v[74:77], v[82:83], off offset:1024
	global_load_dwordx4 v[78:81], v[82:83], off offset:2048
	v_add_u32_e32 v64, s4, v64
	global_load_dwordx4 v[82:85], v[82:83], off offset:3072
	v_mul_hi_i32_i24_e32 v145, 0x1800, v60
	v_mul_i32_i24_e32 v144, 0x1800, v60
	v_lshlrev_b64 v[144:145], 2, v[144:145]
	v_lshl_add_u64 v[146:147], v[54:55], 0, v[144:145]
	v_lshl_add_u64 v[144:145], v[52:53], 0, v[144:145]
	global_load_dwordx4 v[112:115], v[144:145], off
	global_load_dwordx4 v[116:119], v[146:147], off
	global_load_dwordx4 v[120:123], v[144:145], off offset:1024
	global_load_dwordx4 v[124:127], v[146:147], off offset:1024
	global_load_dwordx4 v[128:131], v[144:145], off offset:2048
	global_load_dwordx4 v[132:135], v[146:147], off offset:2048
	global_load_dwordx4 v[136:139], v[144:145], off offset:3072
	global_load_dwordx4 v[140:143], v[146:147], off offset:3072
	s_waitcnt vmcnt(15)
	v_lshlrev_b32_e32 v88, 16, v46
	s_waitcnt vmcnt(14)
	v_lshlrev_b32_e32 v94, 16, v48
	v_and_b32_e32 v95, 0xffff0000, v48
	v_and_b32_e32 v89, 0xffff0000, v46
	v_pk_mul_f32 v[96:97], v[94:95], v[94:95]
	v_lshlrev_b32_e32 v98, 16, v49
	v_and_b32_e32 v99, 0xffff0000, v49
	v_pk_mul_f32 v[90:91], v[88:89], v[88:89]
	v_lshlrev_b32_e32 v92, 16, v47
	v_and_b32_e32 v93, 0xffff0000, v47
	v_pk_mul_f32 v[48:49], v[98:99], v[98:99]
	v_add_f32_e32 v0, v96, v97
	v_pk_mul_f32 v[46:47], v[92:93], v[92:93]
	v_add_f32_e32 v0, v48, v0
	v_add_f32_e32 v48, v90, v91
	s_waitcnt vmcnt(13)
	v_lshlrev_b32_e32 v100, 16, v62
	v_and_b32_e32 v101, 0xffff0000, v62
	v_add_f32_e32 v46, v46, v48
	v_pk_mul_f32 v[102:103], v[100:101], v[100:101]
	v_lshlrev_b32_e32 v62, 16, v63
	v_and_b32_e32 v63, 0xffff0000, v63
	v_add_f32_e32 v0, v49, v0
	v_add_f32_e32 v46, v47, v46
	v_pk_mul_f32 v[104:105], v[62:63], v[62:63]
	v_add_f32_e32 v0, v46, v0
	v_add_f32_e32 v46, v102, v103
	s_waitcnt vmcnt(12)
	v_lshlrev_b32_e32 v106, 16, v86
	v_and_b32_e32 v107, 0xffff0000, v86
	v_add_f32_e32 v46, v104, v46
	v_pk_mul_f32 v[108:109], v[106:107], v[106:107]
	v_lshlrev_b32_e32 v86, 16, v87
	v_and_b32_e32 v87, 0xffff0000, v87
	v_add_f32_e32 v46, v105, v46
	v_pk_mul_f32 v[110:111], v[86:87], v[86:87]
	v_add_f32_e32 v0, v0, v46
	v_add_f32_e32 v46, v108, v109
	v_add_f32_e32 v46, v110, v46
	v_add_f32_e32 v46, v111, v46
	v_add_f32_e32 v0, v0, v46
	s_nop 1
	v_add_f32_dpp v0, v0, v0 quad_perm:[1,0,3,2] row_mask:0xf bank_mask:0xf bound_ctrl:1
	s_nop 1
	v_add_f32_dpp v0, v0, v0 quad_perm:[2,3,0,1] row_mask:0xf bank_mask:0xf bound_ctrl:1
	s_nop 1
	v_add_f32_dpp v0, v0, v0 row_half_mirror row_mask:0xf bank_mask:0xf bound_ctrl:1
	s_nop 1
	v_add_f32_dpp v0, v0, v0 row_mirror row_mask:0xf bank_mask:0xf bound_ctrl:1
	v_mov_b32_e32 v46, v0
	s_nop 1
	v_permlane16_swap_b32_e32 v0, v46
	v_add_f32_e32 v0, v0, v46
	v_mov_b32_e32 v46, v0
	s_nop 1
	v_permlane32_swap_b32_e32 v0, v46
	v_add_f32_e32 v0, v0, v46
	v_fmamk_f32 v0, v0, 0x3a800000, v254
	v_cmp_gt_f32_e32 vcc, s77, v0
	v_mul_f32_e32 v46, 0x4b800000, v0
	s_nop 0
	v_cndmask_b32_e32 v0, v0, v46, vcc
	v_rsq_f32_e32 v0, v0
	s_nop 0
	v_mul_f32_e32 v46, 0x45800000, v0
	v_cndmask_b32_e32 v0, v0, v46, vcc
	v_pk_mul_f32 v[46:47], v[0:1], v[88:89] op_sel_hi:[0,1]
	s_waitcnt vmcnt(11)
	v_pk_mul_f32 v[42:43], v[42:43], v[46:47]
	s_nop 0
	v_pk_fma_f32 v[46:47], v[2:3], v[42:43], v[34:35]
	v_pk_mul_f32 v[34:35], v[0:1], v[92:93] op_sel_hi:[0,1]
	v_pk_mul_f32 v[34:35], v[44:45], v[34:35]
	s_nop 0
	v_pk_fma_f32 v[48:49], v[4:5], v[34:35], v[36:37]
	v_pk_mul_f32 v[34:35], v[0:1], v[94:95] op_sel_hi:[0,1]
	s_waitcnt vmcnt(10)
	v_pk_mul_f32 v[34:35], v[74:75], v[34:35]
	v_pk_mul_f32 v[36:37], v[0:1], v[86:87] op_sel_hi:[0,1]
	v_pk_fma_f32 v[42:43], v[34:35], v[6:7], v[38:39]
	v_pk_mul_f32 v[34:35], v[0:1], v[98:99] op_sel_hi:[0,1]
	v_pk_mul_f32 v[34:35], v[76:77], v[34:35]
	s_waitcnt vmcnt(8)
; DI uint2 pack4(f32x4 v) { uint2 r; r.x = pack2(v[0], v[1]); r.y = pack2(v[2], v[3]); return r; }
; DI void rowwise_phase(const float* __restrict__ xin, float* __restrict__ xout, const u16* __restrict__ tbuf, ...
;     ...
; #pragma unroll
;     for (int i = 0; i < 4; ++i) { const f32x4 t_ = {xv[i].x, xv[i].y, xv[i].z, xv[i].w}; __builtin_nontemporal_store(t_, (f32x4*)(xout + (size_t)row * 1024 + i * 256 + lane * 4)); }
;     if (hbuf) {
;       float ss = 0.f;
; #pragma unroll
;       for (int i = 0; i < 4; ++i) ss += xv[i].x * xv[i].x + xv[i].y * xv[i].y + xv[i].z * xv[i].z + xv[i].w * xv[i].w;
;       ss = wave_sum(ss);
;       const float rstd = rsqrtf(ss * (1.f / 1024.f) + 1e-6f);
; #pragma unroll
;       for (int i = 0; i < 4; ++i) {
;         const int c = i * 256 + lane * 4;
;         const float4 g = *(const float4*)(pre_gain + c);
;         const float4 s1 = *(const float4*)(sc + (size_t)b * 6144 + c);
;         const float4 s0 = *(const float4*)(sh + (size_t)b * 6144 + c);
;         f32x4 h;
;         h[0] = xv[i].x * rstd * g.x * (1.f + s1.x) + s0.x; h[1] = xv[i].y * rstd * g.y * (1.f + s1.y) + s0.y;
;         h[2] = xv[i].z * rstd * g.z * (1.f + s1.z) + s0.z; h[3] = xv[i].w * rstd * g.w * (1.f + s1.w) + s0.w;
;         *(uint2*)(hbuf + (size_t)row * 1024 + c) = pack4(h);
;       }
	v_pk_mul_f32 v[36:37], v[36:37], v[84:85]
	v_pk_fma_f32 v[44:45], v[34:35], v[8:9], v[40:41]
	v_pk_mul_f32 v[34:35], v[0:1], v[100:101] op_sel_hi:[0,1]
	v_pk_mul_f32 v[34:35], v[34:35], v[78:79]
	v_pk_fma_f32 v[36:37], v[36:37], v[16:17], v[72:73]
	v_pk_fma_f32 v[38:39], v[34:35], v[10:11], v[66:67]
	v_pk_mul_f32 v[34:35], v[0:1], v[62:63] op_sel_hi:[0,1]
	v_pk_mul_f32 v[34:35], v[34:35], v[80:81]
	v_pk_mul_f32 v[62:63], v[46:47], v[46:47]
	v_pk_fma_f32 v[40:41], v[34:35], v[12:13], v[68:69]
	v_pk_mul_f32 v[34:35], v[0:1], v[106:107] op_sel_hi:[0,1]
	v_pk_mul_f32 v[34:35], v[34:35], v[82:83]
	v_pk_mul_f32 v[68:69], v[42:43], v[42:43]
	v_pk_fma_f32 v[34:35], v[34:35], v[14:15], v[70:71]
	v_pk_mul_f32 v[66:67], v[48:49], v[48:49]
	v_pk_mul_f32 v[70:71], v[44:45], v[44:45]
	v_add_f32_e32 v0, v68, v69
	v_add_f32_e32 v61, v62, v63
	v_add_f32_e32 v0, v0, v70
	v_add_f32_e32 v61, v66, v61
	v_pk_mul_f32 v[72:73], v[38:39], v[38:39]
	v_add_f32_e32 v0, v0, v71
	v_add_f32_e32 v61, v67, v61
	v_pk_mul_f32 v[74:75], v[40:41], v[40:41]
	v_add_f32_e32 v0, v61, v0
	v_add_f32_e32 v61, v72, v73
	v_add_f32_e32 v61, v61, v74
	v_pk_mul_f32 v[76:77], v[34:35], v[34:35]
	v_add_f32_e32 v61, v61, v75
	v_pk_mul_f32 v[78:79], v[36:37], v[36:37]
	v_add_f32_e32 v0, v0, v61
	v_add_f32_e32 v61, v76, v77
	v_add_f32_e32 v61, v61, v78
	v_add_f32_e32 v61, v61, v79
	v_add_f32_e32 v0, v0, v61
	global_store_dwordx4 v[56:57], v[46:49], off offset:-2048 nt
	global_store_dwordx4 v[56:57], v[42:45], off offset:-1024 nt
	global_store_dwordx4 v[56:57], v[38:41], off nt
	global_store_dwordx4 v[56:57], v[34:37], off offset:1024 nt
	v_add_f32_dpp v0, v0, v0 quad_perm:[1,0,3,2] row_mask:0xf bank_mask:0xf bound_ctrl:1
	v_lshl_add_u64 v[56:57], v[56:57], 0, s[6:7]
	s_nop 0
	v_add_f32_dpp v0, v0, v0 quad_perm:[2,3,0,1] row_mask:0xf bank_mask:0xf bound_ctrl:1
	s_nop 1
	v_add_f32_dpp v0, v0, v0 row_half_mirror row_mask:0xf bank_mask:0xf bound_ctrl:1
	s_nop 1
	v_add_f32_dpp v0, v0, v0 row_mirror row_mask:0xf bank_mask:0xf bound_ctrl:1
	v_mov_b32_e32 v61, v0
	s_nop 1
	v_permlane16_swap_b32_e32 v0, v61
	v_add_f32_e32 v0, v0, v61
	v_mov_b32_e32 v61, v0
	s_nop 1
	v_permlane32_swap_b32_e32 v0, v61
	v_add_f32_e32 v0, v0, v61
	v_fmamk_f32 v0, v0, 0x3a800000, v254
	v_cmp_gt_f32_e32 vcc, s77, v0
	v_mul_f32_e32 v61, 0x4b800000, v0
	s_nop 0
	v_cndmask_b32_e32 v0, v0, v61, vcc
	v_rsq_f32_e32 v0, v0
	s_nop 0
	v_mul_f32_e32 v61, 0x45800000, v0
	v_cndmask_b32_e32 v0, v0, v61, vcc
	v_pk_mul_f32 v[46:47], v[46:47], v[0:1] op_sel_hi:[1,0]
	v_pk_mul_f32 v[48:49], v[48:49], v[0:1] op_sel_hi:[1,0]
	v_pk_mul_f32 v[46:47], v[18:19], v[46:47]
	v_pk_mul_f32 v[48:49], v[20:21], v[48:49]
	v_pk_mul_f32 v[42:43], v[42:43], v[0:1] op_sel_hi:[1,0]
	v_pk_mul_f32 v[44:45], v[44:45], v[0:1] op_sel_hi:[1,0]
	v_pk_mul_f32 v[42:43], v[42:43], v[22:23]
	v_pk_mul_f32 v[44:45], v[44:45], v[24:25]
	v_pk_mul_f32 v[38:39], v[38:39], v[0:1] op_sel_hi:[1,0]
	v_pk_mul_f32 v[40:41], v[40:41], v[0:1] op_sel_hi:[1,0]
	v_pk_mul_f32 v[38:39], v[38:39], v[26:27]
	v_pk_mul_f32 v[40:41], v[40:41], v[28:29]
	v_pk_mul_f32 v[34:35], v[34:35], v[0:1] op_sel_hi:[1,0]
	v_pk_mul_f32 v[36:37], v[36:37], v[0:1] op_sel_hi:[1,0]
	v_pk_mul_f32 v[34:35], v[34:35], v[30:31]
	v_pk_mul_f32 v[36:37], v[36:37], v[32:33]
	v_cmp_lt_i32_e32 vcc, s84, v64
	s_or_b64 s[10:11], vcc, s[10:11]
	s_waitcnt vmcnt(4)
	v_pk_add_f32 v[112:113], v[112:113], 1.0 op_sel_hi:[1,0]
	v_pk_add_f32 v[114:115], v[114:115], 1.0 op_sel_hi:[1,0]
	v_pk_fma_f32 v[46:47], v[112:113], v[46:47], v[116:117]
	v_pk_fma_f32 v[48:49], v[114:115], v[48:49], v[118:119]
	s_nop 0
	v_cvt_pk_bf16_f32 v46, v46, v47
	v_cvt_pk_bf16_f32 v47, v48, v49
	global_store_dwordx2 v[58:59], v[46:47], off offset:-1540
	v_pk_add_f32 v[120:121], v[120:121], 1.0 op_sel_hi:[1,0]
	v_pk_add_f32 v[122:123], v[122:123], 1.0 op_sel_hi:[1,0]
	v_pk_fma_f32 v[42:43], v[120:121], v[42:43], v[124:125]
	v_pk_fma_f32 v[44:45], v[122:123], v[44:45], v[126:127]
	s_nop 0
	v_cvt_pk_bf16_f32 v42, v42, v43
	v_cvt_pk_bf16_f32 v43, v44, v45
	global_store_dwordx2 v[58:59], v[42:43], off offset:-1028
	v_pk_add_f32 v[128:129], v[128:129], 1.0 op_sel_hi:[1,0]
	v_pk_add_f32 v[130:131], v[130:131], 1.0 op_sel_hi:[1,0]
	v_pk_fma_f32 v[38:39], v[128:129], v[38:39], v[132:133]
	v_pk_fma_f32 v[40:41], v[130:131], v[40:41], v[134:135]
	s_nop 0
	v_cvt_pk_bf16_f32 v38, v38, v39
	v_cvt_pk_bf16_f32 v39, v40, v41
	global_store_dwordx2 v[58:59], v[38:39], off offset:-516
	v_pk_add_f32 v[136:137], v[136:137], 1.0 op_sel_hi:[1,0]
	v_pk_add_f32 v[138:139], v[138:139], 1.0 op_sel_hi:[1,0]
	v_pk_fma_f32 v[34:35], v[136:137], v[34:35], v[140:141]
	v_pk_fma_f32 v[36:37], v[138:139], v[36:37], v[142:143]
	s_nop 0
	v_cvt_pk_bf16_f32 v34, v34, v35
	v_cvt_pk_bf16_f32 v35, v36, v37
	global_store_dwordx2 v[58:59], v[34:35], off offset:-4
	v_lshl_add_u64 v[58:59], v[58:59], 0, s[8:9]
	s_andn2_b64 exec, exec, s[10:11]
	s_cbranch_execnz .LBB0_1779
